# nt on the residual-stream x stores of norm B / norm C (reuse distance beyond the MALL)
# baseline (speedup 1.0000x reference)
; DI void phase_norm(const Frame& F0, int nrows, const void* xlat, const void* xctx, int xin_bf16, const bf16* Y, const float* gainY, const float* gate  ,
;                    void* Xout_lat, void* Xout_ctx, int xout_bf16, bf16* Hout, const float* gainH, const float* shift, const float* scale) {
;     ...
;         if (Y) {
;             f32x4 y[8]; float ss = 0.f;
; #pragma unroll
;             for (int j = 0; j < 8; ++j) { y[j] = (f32x4){bflo(yb[j].x), bfhi(yb[j].x), bflo(yb[j].y), bfhi(yb[j].y)};
;                 ss += (y[j].x * y[j].x + y[j].y * y[j].y) + (y[j].z * y[j].z + y[j].w * y[j].w); }
;             const float rs = __builtin_amdgcn_rsqf(wave_sum(ss) * (1.0f / DM) + EPS);
; #pragma unroll
;             for (int j = 0; j < 8; ++j) v[j] = v[j] + gt[j] * (y[j] * rs);
;         }
;         if (Xout_lat) {
;             if (xout_bf16) { bf16* xo = R < NLAT ? (bf16*)Xout_lat + (size_t)R * DM : (bf16*)Xout_ctx + (size_t)(R - NLAT) * DM;
.LBB0_1077:
	v_lshlrev_b32_e32 v226, 16, v206
	v_and_b32_e32 v227, 0xffff0000, v206
	v_lshlrev_b32_e32 v206, 16, v207
	v_and_b32_e32 v207, 0xffff0000, v207
	v_mul_f32_e32 v228, v207, v207
	v_lshlrev_b32_e32 v231, 16, v205
	v_lshlrev_b32_e32 v230, 16, v204
	v_and_b32_e32 v205, 0xffff0000, v205
	v_and_b32_e32 v204, 0xffff0000, v204
	v_lshlrev_b32_e32 v237, 16, v200
	v_mul_f32_e32 v236, v227, v227
	v_pk_fma_f32 v[228:229], v[206:207], v[206:207], v[228:229] op_sel_hi:[1,1,0]
	v_pk_mul_f32 v[232:233], v[204:205], v[204:205]
	v_pk_fma_f32 v[240:241], v[226:227], v[226:227], v[236:237] op_sel_hi:[1,1,0]
	v_pk_fma_f32 v[232:233], v[230:231], v[230:231], v[232:233]
	v_and_b32_e32 v239, 0xffff0000, v200
	v_mov_b32_e32 v236, v240
	v_mov_b32_e32 v242, v228
	v_mov_b32_e32 v243, v237
	v_mul_f32_e32 v213, v239, v239
	v_pk_add_f32 v[228:229], v[240:241], v[228:229]
	v_pk_mul_f32 v[240:241], v[236:237], v[242:243]
	v_pk_add_f32 v[232:233], v[232:233], v[232:233] op_sel:[0,1] op_sel_hi:[1,0]
	v_lshlrev_b32_e32 v234, 16, v202
	v_and_b32_e32 v235, 0xffff0000, v202
	v_lshlrev_b32_e32 v202, 16, v203
	v_and_b32_e32 v203, 0xffff0000, v203
	v_mov_b32_e32 v229, v241
	v_mov_b32_e32 v233, v213
	v_lshlrev_b32_e32 v200, 16, v201
	v_and_b32_e32 v201, 0xffff0000, v201
	v_pk_add_f32 v[228:229], v[228:229], v[232:233]
	v_mul_f32_e32 v232, v235, v235
	v_mul_f32_e32 v236, v203, v203
	v_mul_f32_e32 v218, v200, v200
	v_mul_f32_e32 v219, v201, v201
	v_pk_fma_f32 v[232:233], v[234:235], v[234:235], v[232:233] op_sel_hi:[1,1,0]
	v_pk_fma_f32 v[240:241], v[202:203], v[202:203], v[236:237] op_sel_hi:[1,1,0]
	v_mov_b32_e32 v233, v218
	v_mov_b32_e32 v241, v219
	v_pk_add_f32 v[232:233], v[232:233], v[240:241]
	v_lshlrev_b32_e32 v243, 16, v197
	v_pk_add_f32 v[228:229], v[228:229], v[232:233]
	v_lshlrev_b32_e32 v233, 16, v199
	v_lshlrev_b32_e32 v232, 16, v198
	v_and_b32_e32 v199, 0xffff0000, v199
	v_and_b32_e32 v198, 0xffff0000, v198
	v_pk_mul_f32 v[240:241], v[198:199], v[198:199]
	v_lshlrev_b32_e32 v242, 16, v196
	v_pk_fma_f32 v[240:241], v[232:233], v[232:233], v[240:241]
	v_and_b32_e32 v197, 0xffff0000, v197
	v_pk_add_f32 v[240:241], v[240:241], v[240:241] op_sel:[0,1] op_sel_hi:[1,0]
	v_and_b32_e32 v196, 0xffff0000, v196
	v_lshlrev_b32_e32 v251, 16, v192
	v_and_b32_e32 v219, 0xffff0000, v192
	v_lshlrev_b32_e32 v220, 16, v193
	v_and_b32_e32 v221, 0xffff0000, v193
	v_pk_add_f32 v[192:193], v[228:229], v[228:229] op_sel:[0,1] op_sel_hi:[1,0]
	v_pk_mul_f32 v[244:245], v[196:197], v[196:197]
	v_lshlrev_b32_e32 v246, 16, v194
	v_and_b32_e32 v247, 0xffff0000, v194
	v_lshlrev_b32_e32 v248, 16, v195
	v_and_b32_e32 v249, 0xffff0000, v195
	v_mov_b32_e32 v250, v192
	v_mov_b32_e32 v194, v240
	v_mov_b32_e32 v195, v251
	v_pk_fma_f32 v[244:245], v[242:243], v[242:243], v[244:245]
	v_pk_add_f32 v[192:193], v[192:193], v[240:241]
	v_pk_mul_f32 v[194:195], v[250:251], v[194:195]
	v_mul_f32_e32 v213, v219, v219
	v_mov_b32_e32 v193, v195
	v_pk_add_f32 v[194:195], v[244:245], v[244:245] op_sel:[0,1] op_sel_hi:[1,0]
	v_mul_f32_e32 v218, v220, v220
	v_mov_b32_e32 v195, v213
	v_pk_add_f32 v[192:193], v[192:193], v[194:195]
	v_mul_f32_e32 v194, v247, v247
	v_pk_fma_f32 v[194:195], v[246:247], v[246:247], v[194:195] op_sel_hi:[1,1,0]
	v_mul_f32_e32 v225, v221, v221
	v_mov_b32_e32 v195, v218
	v_mul_f32_e32 v218, v249, v249
	v_pk_fma_f32 v[228:229], v[248:249], v[248:249], v[218:219] op_sel_hi:[1,1,0]
	v_mov_b32_e32 v238, v237
	v_mov_b32_e32 v229, v225
	v_pk_add_f32 v[194:195], v[194:195], v[228:229]
	v_mov_b32_e32 v218, v251
	v_pk_add_f32 v[192:193], v[192:193], v[194:195]
	s_add_i32 s4, s0, 0xffffe000
	v_add_f32_e32 v192, v192, v193
	ds_bpermute_b32 v193, v2, v192
	s_ashr_i32 s1, s0, 31
	s_cmpk_lt_i32 s0, 0x2000
	s_cselect_b32 s5, s1, 0
	s_cselect_b32 s4, s0, s4
	s_waitcnt lgkmcnt(0)
	v_add_f32_e32 v192, v192, v193
	ds_bpermute_b32 v193, v208, v192
	s_cselect_b32 s6, s19, s21
	s_cselect_b32 s7, s18, s20
	s_lshl_b64 s[4:5], s[4:5], 12
	s_add_u32 s4, s7, s4
	s_waitcnt lgkmcnt(0)
	v_add_f32_e32 v192, v192, v193
	ds_bpermute_b32 v193, v209, v192
	s_addc_u32 s5, s6, s5
	s_lshl_b64 s[0:1], s[0:1], 12
	s_addk_i32 s28, 0x400
	s_addk_i32 s29, 0x400
	s_waitcnt lgkmcnt(0)
	v_add_f32_e32 v192, v192, v193
	ds_bpermute_b32 v193, v210, v192
	s_cmp_lg_u32 s16, s25
	s_waitcnt lgkmcnt(0)
	v_add_f32_e32 v192, v192, v193
	ds_bpermute_b32 v193, v211, v192
	s_waitcnt lgkmcnt(0)
	v_add_f32_e32 v192, v192, v193
	ds_bpermute_b32 v193, v212, v192
	s_waitcnt lgkmcnt(0)
; #define GAS __attribute__((address_space(1)))
; DI unsigned pk2(float lo, float hi) { f32x2_t v = {lo, hi}; bf16x2_t b = __builtin_convertvector(v, bf16x2_t); return __builtin_bit_cast(unsigned, b); }
; DI void phase_norm(const Frame& F0, int nrows, const void* xlat, const void* xctx, int xin_bf16, const bf16* Y, const float* gainY, const float* gate  ,
;                    void* Xout_lat, void* Xout_ctx, int xout_bf16, bf16* Hout, const float* gainH, const float* shift, const float* scale) {
;     ...
;             const float rs = __builtin_amdgcn_rsqf(wave_sum(ss) * (1.0f / DM) + EPS);
; #pragma unroll
;             for (int j = 0; j < 8; ++j) v[j] = v[j] + gt[j] * (y[j] * rs);
;         }
;         if (Xout_lat) {
;             if (xout_bf16) { bf16* xo = R < NLAT ? (bf16*)Xout_lat + (size_t)R * DM : (bf16*)Xout_ctx + (size_t)(R - NLAT) * DM;
; #pragma unroll
;                 for (int j = 0; j < 8; ++j) { v2u o; o.x = pk2(v[j].x, v[j].y); o.y = pk2(v[j].z, v[j].w); *(GAS v2u*)(xo + j * 256 + co) = o; } }
;             else { float* xo = R < NLAT ? (float*)Xout_lat + (size_t)R * DM : (float*)Xout_ctx + (size_t)(R - NLAT) * DM;
; #pragma unroll
;                 for (int j = 0; j < 8; ++j) *(GAS f32x4*)(xo + j * 256 + co) = v[j]; } }
;         if (Hout) {
;             float ss = 0.f;
; #pragma unroll
;             for (int j = 0; j < 8; ++j) ss += (v[j].x * v[j].x + v[j].y * v[j].y) + (v[j].z * v[j].z + v[j].w * v[j].w);
;             const float rs = __builtin_amdgcn_rsqf(wave_sum(ss) * (1.0f / DM) + EPS);
	v_add_f32_e32 v192, v192, v193
	v_fmamk_f32 v192, v192, 0x3a000000, v223
	v_rsq_f32_e32 v228, v192
	s_nop 0
	v_pk_mul_f32 v[192:193], v[228:229], v[226:227] op_sel_hi:[0,1]
	v_pk_mul_f32 v[194:195], v[228:229], v[206:207] op_sel_hi:[0,1]
	v_pk_fma_f32 v[192:193], v[16:17], v[192:193], v[120:121]
	v_mov_b32_e32 v120, v230
	v_mov_b32_e32 v121, v204
	v_mov_b32_e32 v204, v231
	v_pk_fma_f32 v[122:123], v[18:19], v[194:195], v[122:123]
	v_pk_mul_f32 v[120:121], v[228:229], v[120:121] op_sel_hi:[0,1]
	v_pk_mul_f32 v[194:195], v[228:229], v[204:205] op_sel_hi:[0,1]
	v_pk_fma_f32 v[118:119], v[14:15], v[194:195], v[118:119]
	v_pk_fma_f32 v[194:195], v[12:13], v[120:121], v[116:117]
	v_pk_mul_f32 v[116:117], v[228:229], v[202:203] op_sel_hi:[0,1]
	v_pk_mul_f32 v[120:121], v[228:229], v[234:235] op_sel_hi:[0,1]
	v_pk_fma_f32 v[116:117], v[10:11], v[116:117], v[130:131]
	v_pk_mul_f32 v[130:131], v[238:239], v[228:229] op_sel_hi:[1,0]
	v_pk_fma_f32 v[128:129], v[8:9], v[120:121], v[128:129]
	v_pk_mul_f32 v[120:121], v[200:201], v[228:229] op_sel_hi:[1,0]
	v_pk_fma_f32 v[130:131], v[4:5], v[130:131], v[124:125]
	v_mov_b32_e32 v124, v232
	v_mov_b32_e32 v125, v198
	v_pk_fma_f32 v[120:121], v[6:7], v[120:121], v[126:127]
	v_pk_mul_f32 v[126:127], v[228:229], v[124:125] op_sel_hi:[0,1]
	v_mov_b32_e32 v198, v233
	v_pk_fma_f32 v[136:137], v[32:33], v[126:127], v[136:137]
	v_mov_b32_e32 v126, v242
	v_mov_b32_e32 v127, v196
	v_pk_mul_f32 v[124:125], v[228:229], v[198:199] op_sel_hi:[0,1]
	v_pk_mul_f32 v[126:127], v[228:229], v[126:127] op_sel_hi:[0,1]
	v_mov_b32_e32 v196, v243
	v_pk_fma_f32 v[124:125], v[34:35], v[124:125], v[138:139]
	v_pk_mul_f32 v[138:139], v[228:229], v[196:197] op_sel_hi:[0,1]
	v_pk_fma_f32 v[196:197], v[28:29], v[126:127], v[132:133]
	v_pk_mul_f32 v[132:133], v[228:229], v[246:247] op_sel_hi:[0,1]
	v_pk_fma_f32 v[134:135], v[30:31], v[138:139], v[134:135]
	v_pk_fma_f32 v[138:139], v[24:25], v[132:133], v[148:149]
	v_pk_mul_f32 v[148:149], v[218:219], v[228:229] op_sel_hi:[1,0]
	v_pk_mul_f32 v[126:127], v[228:229], v[248:249] op_sel_hi:[0,1]
	v_pk_mul_f32 v[132:133], v[220:221], v[228:229] op_sel_hi:[1,0]
	v_pk_fma_f32 v[140:141], v[20:21], v[148:149], v[140:141]
	v_mov_b32_e32 v148, v193
	v_mov_b32_e32 v149, v195
	v_pk_fma_f32 v[126:127], v[26:27], v[126:127], v[150:151]
	v_pk_fma_f32 v[132:133], v[22:23], v[132:133], v[142:143]
	v_mov_b32_e32 v142, v192
	v_mov_b32_e32 v143, v194
	v_pk_mul_f32 v[148:149], v[148:149], v[148:149]
	v_mov_b32_e32 v150, v123
	v_mov_b32_e32 v151, v119
	v_pk_fma_f32 v[142:143], v[142:143], v[142:143], v[148:149]
	v_mov_b32_e32 v148, v122
	v_mov_b32_e32 v149, v118
	v_pk_mul_f32 v[150:151], v[150:151], v[150:151]
	v_pk_fma_f32 v[148:149], v[148:149], v[148:149], v[150:151]
	v_pk_mul_f32 v[150:151], v[128:129], v[128:129]
	v_pk_add_f32 v[142:143], v[142:143], v[148:149]
	v_pk_mul_f32 v[148:149], v[116:117], v[116:117]
	v_pk_add_f32 v[142:143], v[142:143], v[142:143] op_sel_hi:[0,1]
	v_pk_mov_b32 v[198:199], v[150:151], v[148:149] op_sel:[1,0]
	v_mov_b32_e32 v151, v149
	v_mul_f32_e32 v142, v130, v130
	v_pk_add_f32 v[148:149], v[198:199], v[150:151]
	v_pk_fma_f32 v[150:151], v[130:131], v[130:131], v[142:143] op_sel_hi:[1,1,0]
	v_mul_f32_e32 v142, v120, v120
	v_pk_add_f32 v[148:149], v[148:149], v[148:149] op_sel_hi:[0,1]
	v_pk_fma_f32 v[198:199], v[120:121], v[120:121], v[142:143] op_sel_hi:[1,1,0]
	v_mul_f32_e32 v150, v136, v136
	v_mul_f32_e32 v198, v137, v137
	v_mul_f32_e32 v148, v124, v124
	v_mul_f32_e32 v142, v125, v125
	v_pk_add_f32 v[150:151], v[150:151], v[198:199]
	v_pk_add_f32 v[142:143], v[148:149], v[142:143]
	v_pk_mul_f32 v[148:149], v[134:135], v[134:135]
	v_pk_add_f32 v[142:143], v[150:151], v[142:143]
	v_pk_mul_f32 v[150:151], v[196:197], v[196:197]
	v_pk_add_f32 v[142:143], v[142:143], v[142:143] op_sel_hi:[0,1]
	v_pk_mov_b32 v[198:199], v[150:151], v[148:149] op_sel:[1,0]
	v_mov_b32_e32 v151, v149
	v_mul_f32_e32 v142, v138, v138
	v_pk_add_f32 v[148:149], v[198:199], v[150:151]
	v_pk_fma_f32 v[150:151], v[138:139], v[138:139], v[142:143] op_sel_hi:[1,1,0]
	v_mul_f32_e32 v142, v126, v126
	v_pk_add_f32 v[148:149], v[148:149], v[148:149] op_sel_hi:[0,1]
	v_pk_fma_f32 v[198:199], v[126:127], v[126:127], v[142:143] op_sel_hi:[1,1,0]
	v_mul_f32_e32 v150, v140, v140
	v_mul_f32_e32 v198, v141, v141
	v_mul_f32_e32 v148, v132, v132
	v_mul_f32_e32 v142, v133, v133
	v_pk_add_f32 v[150:151], v[150:151], v[198:199]
	v_pk_add_f32 v[142:143], v[148:149], v[142:143]
	v_cvt_pk_bf16_f32 v148, v192, v193
	v_pk_add_f32 v[142:143], v[150:151], v[142:143]
	v_add_f32_e32 v149, v142, v143
	ds_bpermute_b32 v150, v2, v149
	v_lshl_add_u64 v[142:143], v[164:165], 1, s[4:5]
	s_waitcnt lgkmcnt(0)
	v_add_f32_e32 v150, v149, v150
	ds_bpermute_b32 v151, v208, v150
	v_cvt_pk_bf16_f32 v149, v122, v123
	global_store_dwordx2 v[142:143], v[148:149], off nt
	v_cvt_pk_bf16_f32 v148, v194, v195
	v_cvt_pk_bf16_f32 v149, v118, v119
	s_waitcnt lgkmcnt(0)
	v_add_f32_e32 v150, v150, v151
	ds_bpermute_b32 v151, v209, v150
	global_store_dwordx2 v[142:143], v[148:149], off offset:512 nt
	v_cvt_pk_bf16_f32 v148, v128, v129
	v_cvt_pk_bf16_f32 v149, v116, v117
	global_store_dwordx2 v[142:143], v[148:149], off offset:1024 nt
	s_waitcnt lgkmcnt(0)
; #define GAS __attribute__((address_space(1)))
; DI unsigned pk2(float lo, float hi) { f32x2_t v = {lo, hi}; bf16x2_t b = __builtin_convertvector(v, bf16x2_t); return __builtin_bit_cast(unsigned, b); }
; DI void phase_norm(const Frame& F0, int nrows, const void* xlat, const void* xctx, int xin_bf16, const bf16* Y, const float* gainY, const float* gate  ,
;                    void* Xout_lat, void* Xout_ctx, int xout_bf16, bf16* Hout, const float* gainH, const float* shift, const float* scale) {
;     ...
;                 for (int j = 0; j < 8; ++j) { v2u o; o.x = pk2(v[j].x, v[j].y); o.y = pk2(v[j].z, v[j].w); *(GAS v2u*)(xo + j * 256 + co) = o; } }
;             else { float* xo = R < NLAT ? (float*)Xout_lat + (size_t)R * DM : (float*)Xout_ctx + (size_t)(R - NLAT) * DM;
; #pragma unroll
;                 for (int j = 0; j < 8; ++j) *(GAS f32x4*)(xo + j * 256 + co) = v[j]; } }
;         if (Hout) {
;             float ss = 0.f;
; #pragma unroll
;             for (int j = 0; j < 8; ++j) ss += (v[j].x * v[j].x + v[j].y * v[j].y) + (v[j].z * v[j].z + v[j].w * v[j].w);
;             const float rs = __builtin_amdgcn_rsqf(wave_sum(ss) * (1.0f / DM) + EPS);
;             v2u o[8];
; #pragma unroll
;             for (int j = 0; j < 8; ++j) { const f32x4 h = (v[j] * rs) * sc[j] + sh[j]; o[j].x = pk2(h.x, h.y); o[j].y = pk2(h.z, h.w); }
; #pragma unroll
;             for (int j = 0; j < 8; ++j) *(GAS v2u*)(Hout + (size_t)R * DM + j * 256 + co) = o[j];
;         }
; #pragma unroll
;         for (int j = 0; j < 8; ++j) { v[j] = vn[j]; yb[j] = ybn[j]; }
	v_add_f32_e32 v150, v150, v151
	ds_bpermute_b32 v151, v210, v150
	v_cvt_pk_bf16_f32 v148, v130, v131
	v_cvt_pk_bf16_f32 v149, v120, v121
	global_store_dwordx2 v[142:143], v[148:149], off offset:1536 nt
	v_cvt_pk_bf16_f32 v148, v136, v137
	s_waitcnt lgkmcnt(0)
	v_add_f32_e32 v150, v150, v151
	ds_bpermute_b32 v151, v211, v150
	v_cvt_pk_bf16_f32 v149, v124, v125
	global_store_dwordx2 v[142:143], v[148:149], off offset:2048 nt
	v_cvt_pk_bf16_f32 v148, v196, v197
	v_cvt_pk_bf16_f32 v149, v134, v135
	s_waitcnt lgkmcnt(0)
	v_add_f32_e32 v150, v150, v151
	ds_bpermute_b32 v151, v212, v150
	global_store_dwordx2 v[142:143], v[148:149], off offset:2560 nt
	v_cvt_pk_bf16_f32 v148, v138, v139
	v_cvt_pk_bf16_f32 v149, v126, v127
	global_store_dwordx2 v[142:143], v[148:149], off offset:3072 nt
	s_waitcnt lgkmcnt(0)
	v_add_f32_e32 v148, v150, v151
	v_fmamk_f32 v148, v148, 0x3a000000, v223
	v_rsq_f32_e32 v148, v148
	v_cvt_pk_bf16_f32 v150, v140, v141
	v_cvt_pk_bf16_f32 v151, v132, v133
	global_store_dwordx2 v[142:143], v[150:151], off offset:3584 nt
	v_pk_mul_f32 v[142:143], v[192:193], v[148:149] op_sel_hi:[1,0]
	v_pk_mul_f32 v[122:123], v[122:123], v[148:149] op_sel_hi:[1,0]
	v_pk_fma_f32 v[142:143], v[56:57], v[142:143], v[36:37]
	v_pk_fma_f32 v[122:123], v[58:59], v[122:123], v[38:39]
	v_cvt_pk_bf16_f32 v142, v142, v143
	v_cvt_pk_bf16_f32 v143, v122, v123
	v_pk_mul_f32 v[122:123], v[194:195], v[148:149] op_sel_hi:[1,0]
	v_pk_mul_f32 v[118:119], v[118:119], v[148:149] op_sel_hi:[1,0]
	v_pk_fma_f32 v[122:123], v[52:53], v[122:123], v[40:41]
	v_pk_fma_f32 v[118:119], v[54:55], v[118:119], v[42:43]
	v_cvt_pk_bf16_f32 v122, v122, v123
	v_cvt_pk_bf16_f32 v123, v118, v119
	v_pk_mul_f32 v[118:119], v[128:129], v[148:149] op_sel_hi:[1,0]
	v_pk_mul_f32 v[116:117], v[116:117], v[148:149] op_sel_hi:[1,0]
	v_pk_fma_f32 v[118:119], v[64:65], v[118:119], v[44:45]
	v_pk_fma_f32 v[116:117], v[66:67], v[116:117], v[46:47]
	v_cvt_pk_bf16_f32 v118, v118, v119
	v_cvt_pk_bf16_f32 v119, v116, v117
	v_pk_mul_f32 v[116:117], v[130:131], v[148:149] op_sel_hi:[1,0]
	v_pk_mul_f32 v[120:121], v[120:121], v[148:149] op_sel_hi:[1,0]
	v_pk_fma_f32 v[116:117], v[60:61], v[116:117], v[48:49]
	v_pk_fma_f32 v[120:121], v[62:63], v[120:121], v[50:51]
	v_cvt_pk_bf16_f32 v116, v116, v117
	v_cvt_pk_bf16_f32 v117, v120, v121
	v_pk_mul_f32 v[120:121], v[136:137], v[148:149] op_sel_hi:[1,0]
	v_pk_mul_f32 v[124:125], v[124:125], v[148:149] op_sel_hi:[1,0]
	v_pk_fma_f32 v[120:121], v[92:93], v[120:121], v[68:69]
	v_pk_fma_f32 v[124:125], v[94:95], v[124:125], v[70:71]
	v_cvt_pk_bf16_f32 v120, v120, v121
	v_cvt_pk_bf16_f32 v121, v124, v125
	v_pk_mul_f32 v[124:125], v[196:197], v[148:149] op_sel_hi:[1,0]
	v_pk_mul_f32 v[128:129], v[134:135], v[148:149] op_sel_hi:[1,0]
	v_pk_fma_f32 v[124:125], v[88:89], v[124:125], v[72:73]
	v_pk_fma_f32 v[128:129], v[90:91], v[128:129], v[74:75]
	v_cvt_pk_bf16_f32 v124, v124, v125
	v_cvt_pk_bf16_f32 v125, v128, v129
	v_pk_mul_f32 v[128:129], v[138:139], v[148:149] op_sel_hi:[1,0]
	v_pk_mul_f32 v[126:127], v[126:127], v[148:149] op_sel_hi:[1,0]
	v_pk_fma_f32 v[128:129], v[100:101], v[128:129], v[76:77]
	v_pk_fma_f32 v[126:127], v[102:103], v[126:127], v[78:79]
	v_cvt_pk_bf16_f32 v128, v128, v129
	v_cvt_pk_bf16_f32 v129, v126, v127
	v_pk_mul_f32 v[126:127], v[140:141], v[148:149] op_sel_hi:[1,0]
	v_pk_mul_f32 v[130:131], v[132:133], v[148:149] op_sel_hi:[1,0]
	v_pk_fma_f32 v[126:127], v[96:97], v[126:127], v[80:81]
	v_pk_fma_f32 v[130:131], v[98:99], v[130:131], v[82:83]
	v_cvt_pk_bf16_f32 v126, v126, v127
	v_cvt_pk_bf16_f32 v127, v130, v131
	v_lshl_add_u64 v[130:131], v[174:175], 0, s[0:1]
	global_store_dwordx2 v[130:131], v[142:143], off
	global_store_dwordx2 v[130:131], v[122:123], off offset:512
	global_store_dwordx2 v[130:131], v[118:119], off offset:1024
	global_store_dwordx2 v[130:131], v[116:117], off offset:1536
	global_store_dwordx2 v[130:131], v[120:121], off offset:2048
	global_store_dwordx2 v[130:131], v[124:125], off offset:2560
	global_store_dwordx2 v[130:131], v[128:129], off offset:3072
	global_store_dwordx2 v[130:131], v[126:127], off offset:3584
	s_waitcnt vmcnt(16)
	s_mov_b64 vcc, s[88:89]
	s_cbranch_vccnz .Lnorm_nounp_B
	v_lshlrev_b32_e32 v84, 16, v86
	v_and_b32_e32 v85, 0xffff0000, v86
	v_lshlrev_b32_e32 v86, 16, v87
	v_and_b32_e32 v87, 0xffff0000, v87
	v_lshlrev_b32_e32 v104, 16, v106
	v_and_b32_e32 v105, 0xffff0000, v106
	v_lshlrev_b32_e32 v106, 16, v107
	v_and_b32_e32 v107, 0xffff0000, v107
	v_lshlrev_b32_e32 v108, 16, v110
	v_and_b32_e32 v109, 0xffff0000, v110
	v_lshlrev_b32_e32 v110, 16, v111
	v_and_b32_e32 v111, 0xffff0000, v111
	v_lshlrev_b32_e32 v112, 16, v114
	v_and_b32_e32 v113, 0xffff0000, v114
	v_lshlrev_b32_e32 v114, 16, v115
	v_and_b32_e32 v115, 0xffff0000, v115
	v_lshlrev_b32_e32 v144, 16, v146
	v_and_b32_e32 v145, 0xffff0000, v146
	v_lshlrev_b32_e32 v146, 16, v147
	v_and_b32_e32 v147, 0xffff0000, v147
	v_lshlrev_b32_e32 v152, 16, v154
	v_and_b32_e32 v153, 0xffff0000, v154
	v_lshlrev_b32_e32 v154, 16, v155
	v_and_b32_e32 v155, 0xffff0000, v155
	v_lshlrev_b32_e32 v156, 16, v158
	v_and_b32_e32 v157, 0xffff0000, v158
	v_lshlrev_b32_e32 v158, 16, v159
	v_and_b32_e32 v159, 0xffff0000, v159
	v_lshlrev_b32_e32 v160, 16, v162
	v_and_b32_e32 v161, 0xffff0000, v162
	v_lshlrev_b32_e32 v162, 16, v163
	v_and_b32_e32 v163, 0xffff0000, v163

; DI void phase_norm(const Frame& F0, int nrows, const void* xlat, const void* xctx, int xin_bf16, const bf16* Y, const float* gainY, const float* gate  ,
;                    void* Xout_lat, void* Xout_ctx, int xout_bf16, bf16* Hout, const float* gainH, const float* shift, const float* scale) {
;     ...
;         if (Y) {
;             f32x4 y[8]; float ss = 0.f;
; #pragma unroll
;             for (int j = 0; j < 8; ++j) { y[j] = (f32x4){bflo(yb[j].x), bfhi(yb[j].x), bflo(yb[j].y), bfhi(yb[j].y)};
;                 ss += (y[j].x * y[j].x + y[j].y * y[j].y) + (y[j].z * y[j].z + y[j].w * y[j].w); }
;             const float rs = __builtin_amdgcn_rsqf(wave_sum(ss) * (1.0f / DM) + EPS);
; #pragma unroll
;             for (int j = 0; j < 8; ++j) v[j] = v[j] + gt[j] * (y[j] * rs);
.LBB0_1375:
	v_lshlrev_b32_e32 v218, 16, v178
	v_and_b32_e32 v219, 0xffff0000, v178
	v_lshlrev_b32_e32 v178, 16, v179
	v_and_b32_e32 v179, 0xffff0000, v179
	v_mul_f32_e32 v2, v179, v179
	v_pk_fma_f32 v[220:221], v[178:179], v[178:179], v[2:3] op_sel_hi:[1,1,0]
	v_mul_f32_e32 v2, v219, v219
	v_lshlrev_b32_e32 v227, 16, v177
	v_lshlrev_b32_e32 v226, 16, v176
	v_and_b32_e32 v177, 0xffff0000, v177
	v_and_b32_e32 v176, 0xffff0000, v176
	v_lshlrev_b32_e32 v233, 16, v168
	v_and_b32_e32 v235, 0xffff0000, v168
	v_lshlrev_b32_e32 v236, 16, v169
	v_and_b32_e32 v237, 0xffff0000, v169
	v_pk_fma_f32 v[168:169], v[218:219], v[218:219], v[2:3] op_sel_hi:[1,1,0]
	v_pk_mul_f32 v[228:229], v[176:177], v[176:177]
	v_mov_b32_e32 v232, v168
	v_mov_b32_e32 v238, v220
	v_mov_b32_e32 v239, v233
	v_pk_fma_f32 v[228:229], v[226:227], v[226:227], v[228:229]
	v_pk_add_f32 v[168:169], v[168:169], v[220:221]
	v_pk_mul_f32 v[220:221], v[232:233], v[238:239]
	v_and_b32_e32 v231, 0xffff0000, v172
	v_mul_f32_e32 v225, v235, v235
	v_mov_b32_e32 v169, v221
	v_pk_add_f32 v[220:221], v[228:229], v[228:229] op_sel:[0,1] op_sel_hi:[1,0]
	v_lshlrev_b32_e32 v230, 16, v172
	v_lshlrev_b32_e32 v172, 16, v173
	v_and_b32_e32 v173, 0xffff0000, v173
	v_mov_b32_e32 v221, v225
	v_mul_f32_e32 v2, v231, v231
	v_pk_add_f32 v[168:169], v[168:169], v[220:221]
	v_pk_fma_f32 v[220:221], v[230:231], v[230:231], v[2:3] op_sel_hi:[1,1,0]
	v_mul_f32_e32 v2, v173, v173
	v_mul_f32_e32 v234, v236, v236
	v_mul_f32_e32 v240, v237, v237
	v_pk_fma_f32 v[228:229], v[172:173], v[172:173], v[2:3] op_sel_hi:[1,1,0]
	v_mov_b32_e32 v221, v234
	v_mov_b32_e32 v229, v240
	v_pk_add_f32 v[220:221], v[220:221], v[228:229]
	v_and_b32_e32 v229, 0xffff0000, v163
	v_and_b32_e32 v228, 0xffff0000, v162
	v_pk_add_f32 v[168:169], v[168:169], v[220:221]
	v_lshlrev_b32_e32 v221, 16, v163
	v_lshlrev_b32_e32 v220, 16, v162
	v_pk_mul_f32 v[162:163], v[228:229], v[228:229]
	v_and_b32_e32 v241, 0xffff0000, v161
	v_pk_fma_f32 v[162:163], v[220:221], v[220:221], v[162:163]
	v_and_b32_e32 v240, 0xffff0000, v160
	v_pk_add_f32 v[162:163], v[162:163], v[162:163] op_sel:[0,1] op_sel_hi:[1,0]
	v_lshlrev_b32_e32 v247, 16, v152
	v_and_b32_e32 v249, 0xffff0000, v152
	v_lshlrev_b32_e32 v250, 16, v153
	v_and_b32_e32 v251, 0xffff0000, v153
	v_pk_add_f32 v[152:153], v[168:169], v[168:169] op_sel:[0,1] op_sel_hi:[1,0]
	v_lshlrev_b32_e32 v239, 16, v161
	v_lshlrev_b32_e32 v238, 16, v160
	v_pk_mul_f32 v[160:161], v[240:241], v[240:241]
	v_lshlrev_b32_e32 v242, 16, v156
	v_and_b32_e32 v243, 0xffff0000, v156
	v_lshlrev_b32_e32 v244, 16, v157
	v_and_b32_e32 v245, 0xffff0000, v157
	v_mov_b32_e32 v246, v152
	v_mov_b32_e32 v156, v162
	v_mov_b32_e32 v157, v247
	v_pk_fma_f32 v[160:161], v[238:239], v[238:239], v[160:161]
	v_pk_add_f32 v[152:153], v[152:153], v[162:163]
	v_pk_mul_f32 v[156:157], v[246:247], v[156:157]
	v_mul_f32_e32 v2, v249, v249
	v_mov_b32_e32 v153, v157
	v_pk_add_f32 v[156:157], v[160:161], v[160:161] op_sel:[0,1] op_sel_hi:[1,0]
	v_mul_f32_e32 v225, v250, v250
	v_mov_b32_e32 v157, v2
	v_mul_f32_e32 v2, v243, v243
	v_pk_add_f32 v[152:153], v[152:153], v[156:157]
	v_pk_fma_f32 v[156:157], v[242:243], v[242:243], v[2:3] op_sel_hi:[1,1,0]
	v_mul_f32_e32 v2, v245, v245
	v_mul_f32_e32 v232, v251, v251
	v_pk_fma_f32 v[160:161], v[244:245], v[244:245], v[2:3] op_sel_hi:[1,1,0]
	v_mov_b32_e32 v157, v225
	v_mov_b32_e32 v161, v232
	v_pk_add_f32 v[156:157], v[156:157], v[160:161]
	v_mov_b32_e32 v234, v233
	v_pk_add_f32 v[152:153], v[152:153], v[156:157]
	v_mov_b32_e32 v248, v247
	v_add_f32_e32 v2, v152, v153
	ds_bpermute_b32 v152, v208, v2
	s_add_i32 s4, s0, 0xffffe000
	s_ashr_i32 s1, s0, 31
	s_cmpk_lt_i32 s0, 0x2000
	s_cselect_b32 s5, s1, 0
	s_waitcnt lgkmcnt(0)
	v_add_f32_e32 v2, v2, v152
	ds_bpermute_b32 v152, v209, v2
	s_cselect_b32 s4, s0, s4
	s_cselect_b32 s10, s19, s25
	s_cselect_b32 s22, s18, s24
	s_lshl_b64 s[4:5], s[4:5], 12
	s_waitcnt lgkmcnt(0)
	v_add_f32_e32 v2, v2, v152
	ds_bpermute_b32 v152, v210, v2
	s_add_u32 s4, s22, s4
	s_addc_u32 s5, s10, s5
	s_lshl_b64 s[0:1], s[0:1], 12
	s_addk_i32 s9, 0x400
	s_waitcnt lgkmcnt(0)
	v_add_f32_e32 v2, v2, v152
	ds_bpermute_b32 v152, v211, v2
	s_addk_i32 s28, 0x400
	s_cmp_eq_u32 s14, s6
	s_waitcnt lgkmcnt(0)
	v_add_f32_e32 v2, v2, v152
	ds_bpermute_b32 v152, v212, v2
	s_waitcnt lgkmcnt(0)
	v_add_f32_e32 v2, v2, v152
	ds_bpermute_b32 v152, v213, v2
	s_waitcnt lgkmcnt(0)
	v_add_f32_e32 v2, v2, v152
	v_fmamk_f32 v2, v2, 0x3a000000, v223
	v_rsq_f32_e32 v2, v2
	s_nop 0
	v_pk_mul_f32 v[156:157], v[2:3], v[218:219] op_sel_hi:[0,1]
	s_waitcnt vmcnt(23)
	v_pk_fma_f32 v[168:169], v[48:49], v[156:157], v[188:189]
	v_mov_b32_e32 v156, v226
	v_mov_b32_e32 v157, v176
	v_pk_mul_f32 v[156:157], v[2:3], v[156:157] op_sel_hi:[0,1]
	v_mov_b32_e32 v176, v227
	v_pk_mul_f32 v[162:163], v[2:3], v[230:231] op_sel_hi:[0,1]
	v_pk_mul_f32 v[160:161], v[2:3], v[176:177] op_sel_hi:[0,1]
	s_waitcnt vmcnt(22)
	v_pk_fma_f32 v[176:177], v[44:45], v[156:157], v[184:185]
	v_pk_mul_f32 v[156:157], v[2:3], v[172:173] op_sel_hi:[0,1]
	s_waitcnt vmcnt(21)
	v_pk_fma_f32 v[172:173], v[40:41], v[162:163], v[180:181]
	v_pk_mul_f32 v[162:163], v[236:237], v[2:3] op_sel_hi:[1,0]
	v_pk_mul_f32 v[152:153], v[2:3], v[178:179] op_sel_hi:[0,1]
	s_waitcnt vmcnt(20)
	v_pk_fma_f32 v[162:163], v[38:39], v[162:163], v[174:175]
	v_mov_b32_e32 v174, v220
	v_mov_b32_e32 v175, v228
	v_pk_mul_f32 v[178:179], v[234:235], v[2:3] op_sel_hi:[1,0]
	v_pk_mul_f32 v[174:175], v[2:3], v[174:175] op_sel_hi:[0,1]
	v_mov_b32_e32 v228, v221
	v_pk_fma_f32 v[170:171], v[36:37], v[178:179], v[170:171]
	v_pk_mul_f32 v[178:179], v[2:3], v[228:229] op_sel_hi:[0,1]
	s_waitcnt vmcnt(19)
; #define GAS __attribute__((address_space(1)))
; DI unsigned pk2(float lo, float hi) { f32x2_t v = {lo, hi}; bf16x2_t b = __builtin_convertvector(v, bf16x2_t); return __builtin_bit_cast(unsigned, b); }
; DI void phase_norm(const Frame& F0, int nrows, const void* xlat, const void* xctx, int xin_bf16, const bf16* Y, const float* gainY, const float* gate  ,
;                    void* Xout_lat, void* Xout_ctx, int xout_bf16, bf16* Hout, const float* gainH, const float* shift, const float* scale) {
;     ...
;             for (int j = 0; j < 8; ++j) v[j] = v[j] + gt[j] * (y[j] * rs);
;         }
;         if (Xout_lat) {
;             if (xout_bf16) { bf16* xo = R < NLAT ? (bf16*)Xout_lat + (size_t)R * DM : (bf16*)Xout_ctx + (size_t)(R - NLAT) * DM;
; #pragma unroll
;                 for (int j = 0; j < 8; ++j) { v2u o; o.x = pk2(v[j].x, v[j].y); o.y = pk2(v[j].z, v[j].w); *(GAS v2u*)(xo + j * 256 + co) = o; } }
;             else { float* xo = R < NLAT ? (float*)Xout_lat + (size_t)R * DM : (float*)Xout_ctx + (size_t)(R - NLAT) * DM;
; #pragma unroll
;                 for (int j = 0; j < 8; ++j) *(GAS f32x4*)(xo + j * 256 + co) = v[j]; } }
;         if (Hout) {
;             float ss = 0.f;
; #pragma unroll
;             for (int j = 0; j < 8; ++j) ss += (v[j].x * v[j].x + v[j].y * v[j].y) + (v[j].z * v[j].z + v[j].w * v[j].w);
;             const float rs = __builtin_amdgcn_rsqf(wave_sum(ss) * (1.0f / DM) + EPS);
	v_pk_fma_f32 v[164:165], v[64:65], v[174:175], v[164:165]
	v_mov_b32_e32 v175, v240
	v_mov_b32_e32 v240, v239
	v_pk_fma_f32 v[166:167], v[66:67], v[178:179], v[166:167]
	v_mov_b32_e32 v174, v238
	v_pk_mul_f32 v[178:179], v[2:3], v[240:241] op_sel_hi:[0,1]
	v_pk_mul_f32 v[174:175], v[2:3], v[174:175] op_sel_hi:[0,1]
	s_waitcnt vmcnt(18)
	v_pk_fma_f32 v[158:159], v[62:63], v[178:179], v[158:159]
	v_pk_mul_f32 v[178:179], v[2:3], v[244:245] op_sel_hi:[0,1]
	v_pk_fma_f32 v[154:155], v[60:61], v[174:175], v[154:155]
	v_pk_mul_f32 v[174:175], v[2:3], v[242:243] op_sel_hi:[0,1]
	s_waitcnt vmcnt(17)
	v_pk_fma_f32 v[150:151], v[58:59], v[178:179], v[150:151]
	v_pk_mul_f32 v[178:179], v[250:251], v[2:3] op_sel_hi:[1,0]
	v_pk_fma_f32 v[152:153], v[50:51], v[152:153], v[190:191]
	v_pk_fma_f32 v[160:161], v[46:47], v[160:161], v[186:187]
	v_pk_fma_f32 v[148:149], v[56:57], v[174:175], v[148:149]
	v_pk_mul_f32 v[174:175], v[248:249], v[2:3] op_sel_hi:[1,0]
	s_waitcnt vmcnt(16)
	v_pk_fma_f32 v[146:147], v[54:55], v[178:179], v[146:147]
	v_mov_b32_e32 v178, v169
	v_mov_b32_e32 v179, v177
	v_pk_fma_f32 v[144:145], v[52:53], v[174:175], v[144:145]
	v_mov_b32_e32 v174, v168
	v_mov_b32_e32 v175, v176
	v_pk_mul_f32 v[178:179], v[178:179], v[178:179]
	v_mov_b32_e32 v180, v153
	v_mov_b32_e32 v181, v161
	v_pk_fma_f32 v[174:175], v[174:175], v[174:175], v[178:179]
	v_mov_b32_e32 v178, v152
	v_mov_b32_e32 v179, v160
	v_pk_mul_f32 v[180:181], v[180:181], v[180:181]
	v_pk_fma_f32 v[156:157], v[42:43], v[156:157], v[182:183]
	v_pk_fma_f32 v[178:179], v[178:179], v[178:179], v[180:181]
	v_pk_mul_f32 v[180:181], v[172:173], v[172:173]
	v_pk_add_f32 v[174:175], v[174:175], v[178:179]
	v_pk_mul_f32 v[178:179], v[156:157], v[156:157]
	v_mul_f32_e32 v2, v170, v170
	v_pk_mov_b32 v[182:183], v[180:181], v[178:179] op_sel:[1,0]
	v_mov_b32_e32 v181, v179
	v_pk_add_f32 v[178:179], v[182:183], v[180:181]
	v_pk_fma_f32 v[180:181], v[170:171], v[170:171], v[2:3] op_sel_hi:[1,1,0]
	v_mul_f32_e32 v2, v162, v162
	v_pk_add_f32 v[174:175], v[174:175], v[174:175] op_sel_hi:[0,1]
	v_pk_add_f32 v[178:179], v[178:179], v[178:179] op_sel_hi:[0,1]
	v_pk_fma_f32 v[182:183], v[162:163], v[162:163], v[2:3] op_sel_hi:[1,1,0]
	v_mul_f32_e32 v180, v164, v164
	v_mul_f32_e32 v182, v165, v165
	v_mul_f32_e32 v178, v166, v166
	v_mul_f32_e32 v174, v167, v167
	v_pk_add_f32 v[180:181], v[180:181], v[182:183]
	v_pk_add_f32 v[174:175], v[178:179], v[174:175]
	v_pk_mul_f32 v[178:179], v[158:159], v[158:159]
	v_pk_add_f32 v[174:175], v[180:181], v[174:175]
	v_pk_mul_f32 v[180:181], v[154:155], v[154:155]
	v_mul_f32_e32 v2, v148, v148
	v_pk_mov_b32 v[182:183], v[180:181], v[178:179] op_sel:[1,0]
	v_mov_b32_e32 v181, v179
	v_pk_add_f32 v[178:179], v[182:183], v[180:181]
	v_pk_fma_f32 v[180:181], v[148:149], v[148:149], v[2:3] op_sel_hi:[1,1,0]
	v_mul_f32_e32 v2, v150, v150
	v_pk_add_f32 v[174:175], v[174:175], v[174:175] op_sel_hi:[0,1]
	v_pk_add_f32 v[178:179], v[178:179], v[178:179] op_sel_hi:[0,1]
	v_pk_fma_f32 v[182:183], v[150:151], v[150:151], v[2:3] op_sel_hi:[1,1,0]
	v_mul_f32_e32 v180, v144, v144
	v_mul_f32_e32 v182, v145, v145
	v_mul_f32_e32 v178, v146, v146
	v_mul_f32_e32 v174, v147, v147
	v_pk_add_f32 v[180:181], v[180:181], v[182:183]
	v_pk_add_f32 v[174:175], v[178:179], v[174:175]
	v_cvt_pk_bf16_f32 v178, v168, v169
	v_pk_add_f32 v[174:175], v[180:181], v[174:175]
	v_mov_b32_e32 v188, v4
	v_add_f32_e32 v2, v174, v175
	ds_bpermute_b32 v179, v208, v2
	v_lshl_add_u64 v[174:175], v[132:133], 1, s[4:5]
	v_mov_b32_e32 v189, v5
	v_mov_b32_e32 v190, v6
	v_mov_b32_e32 v191, v7
	s_waitcnt lgkmcnt(0)
	v_add_f32_e32 v2, v2, v179
	ds_bpermute_b32 v180, v209, v2
	v_cvt_pk_bf16_f32 v179, v152, v153
	global_store_dwordx2 v[174:175], v[178:179], off nt
	v_cvt_pk_bf16_f32 v178, v176, v177
	v_cvt_pk_bf16_f32 v179, v160, v161
	s_waitcnt lgkmcnt(0)
	v_add_f32_e32 v2, v2, v180
	ds_bpermute_b32 v180, v210, v2
	global_store_dwordx2 v[174:175], v[178:179], off offset:512 nt
	v_cvt_pk_bf16_f32 v178, v172, v173
	v_cvt_pk_bf16_f32 v179, v156, v157
	global_store_dwordx2 v[174:175], v[178:179], off offset:1024 nt
	s_waitcnt lgkmcnt(0)
	v_add_f32_e32 v2, v2, v180
	ds_bpermute_b32 v180, v211, v2
	v_cvt_pk_bf16_f32 v178, v170, v171
	v_cvt_pk_bf16_f32 v179, v162, v163
	global_store_dwordx2 v[174:175], v[178:179], off offset:1536 nt
	v_cvt_pk_bf16_f32 v178, v164, v165
	s_waitcnt lgkmcnt(0)
	v_add_f32_e32 v2, v2, v180
	ds_bpermute_b32 v180, v212, v2
	v_cvt_pk_bf16_f32 v179, v166, v167
	global_store_dwordx2 v[174:175], v[178:179], off offset:2048 nt
	v_cvt_pk_bf16_f32 v178, v154, v155
	v_cvt_pk_bf16_f32 v179, v158, v159
	s_waitcnt lgkmcnt(0)
; #define GAS __attribute__((address_space(1)))
; DI unsigned pk2(float lo, float hi) { f32x2_t v = {lo, hi}; bf16x2_t b = __builtin_convertvector(v, bf16x2_t); return __builtin_bit_cast(unsigned, b); }
; DI void phase_norm(const Frame& F0, int nrows, const void* xlat, const void* xctx, int xin_bf16, const bf16* Y, const float* gainY, const float* gate  ,
;                    void* Xout_lat, void* Xout_ctx, int xout_bf16, bf16* Hout, const float* gainH, const float* shift, const float* scale) {
;     ...
;                 for (int j = 0; j < 8; ++j) { v2u o; o.x = pk2(v[j].x, v[j].y); o.y = pk2(v[j].z, v[j].w); *(GAS v2u*)(xo + j * 256 + co) = o; } }
;             else { float* xo = R < NLAT ? (float*)Xout_lat + (size_t)R * DM : (float*)Xout_ctx + (size_t)(R - NLAT) * DM;
; #pragma unroll
;                 for (int j = 0; j < 8; ++j) *(GAS f32x4*)(xo + j * 256 + co) = v[j]; } }
;         if (Hout) {
;             float ss = 0.f;
; #pragma unroll
;             for (int j = 0; j < 8; ++j) ss += (v[j].x * v[j].x + v[j].y * v[j].y) + (v[j].z * v[j].z + v[j].w * v[j].w);
;             const float rs = __builtin_amdgcn_rsqf(wave_sum(ss) * (1.0f / DM) + EPS);
;             v2u o[8];
; #pragma unroll
;             for (int j = 0; j < 8; ++j) { const f32x4 h = (v[j] * rs) * sc[j] + sh[j]; o[j].x = pk2(h.x, h.y); o[j].y = pk2(h.z, h.w); }
; #pragma unroll
;             for (int j = 0; j < 8; ++j) *(GAS v2u*)(Hout + (size_t)R * DM + j * 256 + co) = o[j];
;         }
; #pragma unroll
;         for (int j = 0; j < 8; ++j) { v[j] = vn[j]; yb[j] = ybn[j]; }
	v_add_f32_e32 v2, v2, v180
	ds_bpermute_b32 v180, v213, v2
	global_store_dwordx2 v[174:175], v[178:179], off offset:2560 nt
	v_cvt_pk_bf16_f32 v178, v148, v149
	v_cvt_pk_bf16_f32 v179, v150, v151
	global_store_dwordx2 v[174:175], v[178:179], off offset:3072 nt
	s_waitcnt lgkmcnt(0)
	v_add_f32_e32 v2, v2, v180
	v_fmamk_f32 v2, v2, 0x3a000000, v223
	v_rsq_f32_e32 v2, v2
	v_cvt_pk_bf16_f32 v178, v144, v145
	v_cvt_pk_bf16_f32 v179, v146, v147
	global_store_dwordx2 v[174:175], v[178:179], off offset:3584 nt
	v_pk_mul_f32 v[168:169], v[168:169], v[2:3] op_sel_hi:[1,0]
	v_pk_mul_f32 v[152:153], v[152:153], v[2:3] op_sel_hi:[1,0]
	s_waitcnt vmcnt(21)
	v_pk_fma_f32 v[168:169], v[88:89], v[168:169], v[68:69]
	v_pk_fma_f32 v[152:153], v[90:91], v[152:153], v[70:71]
	v_cvt_pk_bf16_f32 v168, v168, v169
	v_cvt_pk_bf16_f32 v169, v152, v153
	v_pk_mul_f32 v[152:153], v[176:177], v[2:3] op_sel_hi:[1,0]
	v_pk_mul_f32 v[160:161], v[160:161], v[2:3] op_sel_hi:[1,0]
	s_waitcnt vmcnt(20)
	v_pk_fma_f32 v[152:153], v[84:85], v[152:153], v[72:73]
	v_pk_fma_f32 v[160:161], v[86:87], v[160:161], v[74:75]
	v_cvt_pk_bf16_f32 v152, v152, v153
	v_cvt_pk_bf16_f32 v153, v160, v161
	v_pk_mul_f32 v[160:161], v[172:173], v[2:3] op_sel_hi:[1,0]
	v_pk_mul_f32 v[156:157], v[156:157], v[2:3] op_sel_hi:[1,0]
	s_waitcnt vmcnt(17)
	v_pk_fma_f32 v[160:161], v[96:97], v[160:161], v[76:77]
	v_pk_fma_f32 v[156:157], v[98:99], v[156:157], v[78:79]
	v_cvt_pk_bf16_f32 v160, v160, v161
	v_cvt_pk_bf16_f32 v161, v156, v157
	v_pk_mul_f32 v[156:157], v[170:171], v[2:3] op_sel_hi:[1,0]
	v_pk_mul_f32 v[162:163], v[162:163], v[2:3] op_sel_hi:[1,0]
	s_waitcnt vmcnt(16)
	v_pk_fma_f32 v[156:157], v[92:93], v[156:157], v[80:81]
	v_pk_fma_f32 v[162:163], v[94:95], v[162:163], v[82:83]
	v_cvt_pk_bf16_f32 v156, v156, v157
	v_cvt_pk_bf16_f32 v157, v162, v163
	v_pk_mul_f32 v[162:163], v[164:165], v[2:3] op_sel_hi:[1,0]
	v_pk_mul_f32 v[164:165], v[166:167], v[2:3] op_sel_hi:[1,0]
	v_pk_mul_f32 v[154:155], v[154:155], v[2:3] op_sel_hi:[1,0]
	v_pk_mul_f32 v[158:159], v[158:159], v[2:3] op_sel_hi:[1,0]
	v_pk_mul_f32 v[148:149], v[148:149], v[2:3] op_sel_hi:[1,0]
	v_pk_mul_f32 v[150:151], v[150:151], v[2:3] op_sel_hi:[1,0]
	v_pk_mul_f32 v[144:145], v[144:145], v[2:3] op_sel_hi:[1,0]
	v_pk_mul_f32 v[146:147], v[146:147], v[2:3] op_sel_hi:[1,0]
	s_waitcnt vmcnt(13)
	v_pk_fma_f32 v[164:165], v[122:123], v[164:165], v[102:103]
	v_pk_fma_f32 v[162:163], v[120:121], v[162:163], v[100:101]
	s_waitcnt vmcnt(12)
	v_pk_fma_f32 v[158:159], v[118:119], v[158:159], v[106:107]
	v_pk_fma_f32 v[154:155], v[116:117], v[154:155], v[104:105]
	s_waitcnt vmcnt(9)
	v_pk_fma_f32 v[150:151], v[130:131], v[150:151], v[110:111]
	v_pk_fma_f32 v[148:149], v[128:129], v[148:149], v[108:109]
	s_waitcnt vmcnt(8)
	v_pk_fma_f32 v[146:147], v[126:127], v[146:147], v[114:115]
	v_pk_fma_f32 v[144:145], v[124:125], v[144:145], v[112:113]
	v_cvt_pk_bf16_f32 v162, v162, v163
	v_cvt_pk_bf16_f32 v163, v164, v165
	v_cvt_pk_bf16_f32 v154, v154, v155
	v_cvt_pk_bf16_f32 v155, v158, v159
	v_cvt_pk_bf16_f32 v148, v148, v149
	v_cvt_pk_bf16_f32 v149, v150, v151
	v_cvt_pk_bf16_f32 v144, v144, v145
	v_cvt_pk_bf16_f32 v145, v146, v147
	v_lshl_add_u64 v[146:147], v[142:143], 0, s[0:1]
	global_store_dwordx2 v[146:147], v[168:169], off
	global_store_dwordx2 v[146:147], v[152:153], off offset:512
	global_store_dwordx2 v[146:147], v[160:161], off offset:1024
	global_store_dwordx2 v[146:147], v[156:157], off offset:1536
	global_store_dwordx2 v[146:147], v[162:163], off offset:2048
	global_store_dwordx2 v[146:147], v[154:155], off offset:2560
	global_store_dwordx2 v[146:147], v[148:149], off offset:3072
	global_store_dwordx2 v[146:147], v[144:145], off offset:3584
	v_mov_b64_e32 v[178:179], v[206:207]
	v_mov_b64_e32 v[176:177], v[204:205]
	v_mov_b64_e32 v[172:173], v[202:203]
	v_mov_b64_e32 v[168:169], v[200:201]
	v_mov_b64_e32 v[162:163], v[198:199]
	v_mov_b64_e32 v[160:161], v[196:197]
	v_mov_b64_e32 v[156:157], v[194:195]
	v_mov_b64_e32 v[152:153], v[192:193]
	v_mov_b32_e32 v184, v8
	v_mov_b32_e32 v185, v9
	v_mov_b32_e32 v186, v10
	v_mov_b32_e32 v187, v11
	v_mov_b32_e32 v180, v12
	v_mov_b32_e32 v181, v13
	v_mov_b32_e32 v182, v14
	v_mov_b32_e32 v183, v15
	v_mov_b32_e32 v170, v16
	v_mov_b32_e32 v171, v17
	v_mov_b32_e32 v174, v18
	v_mov_b32_e32 v175, v19
	v_mov_b32_e32 v164, v20
	v_mov_b32_e32 v165, v21
	v_mov_b32_e32 v166, v22
	v_mov_b32_e32 v167, v23
	v_mov_b32_e32 v154, v24
	v_mov_b32_e32 v155, v25
	v_mov_b32_e32 v158, v26
	v_mov_b32_e32 v159, v27
	v_mov_b32_e32 v148, v28
	v_mov_b32_e32 v149, v29
	v_mov_b32_e32 v150, v30
	v_mov_b32_e32 v151, v31
	v_mov_b32_e32 v144, v32
	v_mov_b32_e32 v145, v33
	v_mov_b32_e32 v146, v34
	v_mov_b32_e32 v147, v35
	s_cbranch_scc1 .LBB0_1343
